# lora_prep (P3): items mapped so each wave holds 8 rows x one 8-chunk group (tanh/sigmoid/plain/zero wave-uniform, group rotated by row block for balance): the masked-out transcendental paths are skipp
# speedup vs baseline: 1.0023x; 1.0023x over previous
.LBB0_268:
	v_lshrrev_b32_e32 v0, 6, v16
	v_mul_hi_u32 v22, v0, s26
	v_lshrrev_b32_e32 v22, 2, v22
	v_add_u32_e32 v0, v0, v22
	v_mul_hi_u32 v18, v0, s26
	v_lshrrev_b32_e32 v18, 2, v18
	v_mul_u32_u24_e32 v18, 6, v18
	v_sub_u32_e32 v18, v0, v18
	v_and_b32_e32 v0, 63, v16
	v_lshlrev_b32_e32 v22, 3, v22
	v_lshrrev_b32_e32 v1, 3, v0
	v_add_u32_e32 v22, v22, v1
	v_and_b32_e32 v0, 7, v0
	v_lshl_add_u32 v18, v18, 3, v0
	v_cmp_gt_u32_e32 vcc, 36, v18
	v_mov_b32_e32 v3, v19
	v_mov_b32_e32 v2, v19
	v_mov_b32_e32 v1, v19
	v_mov_b32_e32 v0, v19
	s_and_saveexec_b64 s[20:21], vcc
	s_cbranch_execz .LBB0_267
	v_mov_b64_e32 v[0:1], s[6:7]
	v_mad_u64_u32 v[0:1], s[2:3], v22, s27, v[0:1]
	v_lshl_add_u64 v[8:9], v[18:19], 4, v[0:1]
	v_add_co_u32_e32 v0, vcc, 0x6d01000, v8
	v_and_b32_e32 v5, 0xfff, v22
	s_nop 0
	v_addc_co_u32_e32 v1, vcc, 0, v9, vcc
	global_load_dwordx4 v[0:3], v[0:1], off offset:2048
	v_mov_b32_e32 v4, 0
	v_cmp_ne_u32_e32 vcc, 0, v5
	v_mov_b32_e32 v5, 0
	v_mov_b32_e32 v6, 0
	v_mov_b32_e32 v7, 0
	s_and_saveexec_b64 s[2:3], vcc
	s_cbranch_execz .LBB0_271
	v_lshl_add_u64 v[4:5], v[8:9], 0, s[16:17]
	v_add_co_u32_e32 v4, vcc, 0xfffff000, v4
	s_nop 1
	v_addc_co_u32_e32 v5, vcc, -1, v5, vcc
	global_load_dwordx4 v[4:7], v[4:5], off offset:-3072
